# K-loops: MFMA-segment barrier issued 2 MFMAs before the block end with s_setprio 3 on the trailing MFMAs (on top of merged priority windows)
# speedup vs baseline: 1.0103x; 1.0103x over previous
; #define PG8_STAGE(bufoff, gbase, voff) do { _Pragma("unroll") for (int _i = 0; _i < 2; ++_i) \
;         __builtin_amdgcn_global_load_lds((const unsigned*)((const char*)(gbase) + (voff)[_i]), (PG8_LAS unsigned*)(lds + (bufoff) + ldsw + _i * 8192), 16, 0, 0); } while (0)
; #define PG8_LDA(dst, b, h) do { _Pragma("unroll") for (int m = 0; m < 4; ++m) _Pragma("unroll") for (int k = 0; k < 2; ++k) dst[m][k] = *(const PG8_LAS bf16x8*)(lds + PG8_SA(b, h) + aoff + m * 2048 + k * 1024); } while (0)
; #define PG8_LDB(dst, b, h) do { _Pragma("unroll") for (int n = 0; n < 2; ++n) _Pragma("unroll") for (int k = 0; k < 2; ++k) dst[n][k] = *(const PG8_LAS bf16x8*)(lds + PG8_SB(b, h) + boff + n * 2048 + k * 1024); } while (0)
; #define PG8_MMA(ai, bj, At, Bt) do { __builtin_amdgcn_s_setprio(1); _Pragma("unroll") for (int m = 0; m < 4; ++m) _Pragma("unroll") for (int n = 0; n < 2; ++n) _Pragma("unroll") for (int k = 0; k < 2; ++k) \
;         acc[ai][bj][m][n] = __builtin_amdgcn_mfma_f32_16x16x32_bf16(Bt[n][k], At[m][k], acc[ai][bj][m][n], 0, 0, 0); __builtin_amdgcn_s_setprio(0); } while (0)
; #define PG8_WAIT_V(n) asm volatile("s_waitcnt vmcnt(" #n ")" ::: "memory")
; #define PG8_WAIT_L(n) asm volatile("s_waitcnt lgkmcnt(" #n ")" ::: "memory")
; #define PG8_BAR __builtin_amdgcn_s_barrier()
; #define PG8_SCHED __builtin_amdgcn_sched_barrier(0)
; template <class Epi, class Sched, bool ALIGN_EPI = false, bool SP2 = false>
; __device__ __forceinline__ void gemm_phase(PG8_LAS unsigned char* lds, const Gemm g, const Sched& S, const Epi& E, int tid_in) {
;     ...
;         for (int t = 0; t < nt; t += 2) {
;             const bool last = (t == nt - 2);
;             const char* a1 = cA + (size_t)(t + 1) * kstep;
;             const char* a2 = last ? nA : cA + (size_t)(t + 2) * kstep; const char* b2 = last ? nB : cB + (size_t)(t + 2) * kstep;
;             const char* a3 = a2 + kstep; const char* b3 = b2 + kstep;
;             if (last && has_next) S.a_ready(nxt);
;             if constexpr (SP2) {
;             PG8_LDB(B0, 0, 0); PG8_LDB(B1, 0, 1); PG8_SCHED; PG8_LDA(At, 0, 0); PG8_STAGE(PG8_SA(1, 1), a1 + hstep, voffA);
;             PG8_WAIT_V(8); PG8_WAIT_L(0); PG8_BAR; PG8_MMA(0, 0, At, B0); PG8_MMA(0, 1, At, B1); PG8_BAR; PG8_SCHED;
;             PG8_LDA(At, 0, 1); PG8_STAGE(PG8_SB(0, 0), b2, voffB); PG8_STAGE(PG8_SB(0, 1), b2 + hstep, voffB); PG8_STAGE(PG8_SA(0, 0), a2, voffA);
.LBB0_219:
	s_add_u32 s0, s24, 0xfffc0080
	s_addc_u32 s1, s25, -1
	s_add_i32 s2, 0, 0x10000
	s_cmp_eq_u32 s55, 12
	s_cselect_b32 s29, s7, s1
	s_cselect_b32 s28, s9, s0
	s_cselect_b32 s27, s17, s54
	s_cselect_b32 s26, s19, s53
	s_add_i32 s3, 0, 0x14000
	v_add_u32_e32 v140, s2, v168
	v_add_u32_e32 v174, s3, v168
	ds_read_b128 v[128:131], v140
	ds_read_b128 v[132:135], v140 offset:1024
	ds_read_b128 v[136:139], v140 offset:2048
	ds_read_b128 v[140:143], v140 offset:3072
	ds_read_b128 v[158:161], v174
	ds_read_b128 v[162:165], v174 offset:1024
	ds_read_b128 v[170:173], v174 offset:2048
	ds_read_b128 v[174:177], v174 offset:3072
	v_lshl_add_u64 v[210:211], s[24:25], 0, v[154:155]
	s_add_i32 m0, s41, 0xc000
	ds_read_b128 v[178:181], v169
	ds_read_b128 v[182:185], v169 offset:1024
	ds_read_b128 v[186:189], v169 offset:2048
	ds_read_b128 v[190:193], v169 offset:3072
	ds_read_b128 v[194:197], v169 offset:4096
	ds_read_b128 v[198:201], v169 offset:5120
	ds_read_b128 v[202:205], v169 offset:6144
	ds_read_b128 v[206:209], v169 offset:7168
	global_load_lds_dwordx4 v[210:211], off
	v_lshl_add_u64 v[210:211], s[24:25], 0, v[156:157]
	s_add_i32 m0, s41, 0xe000
	s_nop 0
	global_load_lds_dwordx4 v[210:211], off
	s_waitcnt vmcnt(8)
	s_waitcnt lgkmcnt(0)
	s_barrier
	s_setprio 1
	s_waitcnt lgkmcnt(0)
	v_mfma_f32_16x16x32_bf16 v[124:127], v[128:131], v[178:181], v[124:127]
	v_mfma_f32_16x16x32_bf16 v[120:123], v[136:139], v[178:181], v[120:123]
	v_mfma_f32_16x16x32_bf16 v[108:111], v[128:131], v[186:189], v[108:111]
	v_mfma_f32_16x16x32_bf16 v[104:107], v[136:139], v[186:189], v[104:107]
	v_mfma_f32_16x16x32_bf16 v[92:95], v[128:131], v[194:197], v[92:95]
	v_mfma_f32_16x16x32_bf16 v[88:91], v[136:139], v[194:197], v[88:91]
	v_mfma_f32_16x16x32_bf16 v[76:79], v[128:131], v[202:205], v[76:79]
	v_mfma_f32_16x16x32_bf16 v[72:75], v[136:139], v[202:205], v[72:75]
	v_mfma_f32_16x16x32_bf16 v[124:127], v[132:135], v[182:185], v[124:127]
	v_mfma_f32_16x16x32_bf16 v[120:123], v[140:143], v[182:185], v[120:123]
	v_mfma_f32_16x16x32_bf16 v[108:111], v[132:135], v[190:193], v[108:111]
	v_mfma_f32_16x16x32_bf16 v[104:107], v[140:143], v[190:193], v[104:107]
	v_mfma_f32_16x16x32_bf16 v[92:95], v[132:135], v[198:201], v[92:95]
	v_mfma_f32_16x16x32_bf16 v[88:91], v[140:143], v[198:201], v[88:91]
	v_mfma_f32_16x16x32_bf16 v[76:79], v[132:135], v[206:209], v[76:79]
	v_mfma_f32_16x16x32_bf16 v[72:75], v[140:143], v[206:209], v[72:75]
	v_mfma_f32_16x16x32_bf16 v[116:119], v[158:161], v[178:181], v[116:119]
	v_mfma_f32_16x16x32_bf16 v[112:115], v[170:173], v[178:181], v[112:115]
	v_mfma_f32_16x16x32_bf16 v[100:103], v[158:161], v[186:189], v[100:103]
	v_mfma_f32_16x16x32_bf16 v[96:99], v[170:173], v[186:189], v[96:99]
	v_mfma_f32_16x16x32_bf16 v[84:87], v[158:161], v[194:197], v[84:87]
	v_mfma_f32_16x16x32_bf16 v[80:83], v[170:173], v[194:197], v[80:83]
	v_mfma_f32_16x16x32_bf16 v[68:71], v[158:161], v[202:205], v[68:71]
	v_mfma_f32_16x16x32_bf16 v[64:67], v[170:173], v[202:205], v[64:67]
	v_mfma_f32_16x16x32_bf16 v[116:119], v[162:165], v[182:185], v[116:119]
	v_mfma_f32_16x16x32_bf16 v[112:115], v[174:177], v[182:185], v[112:115]
	v_mfma_f32_16x16x32_bf16 v[100:103], v[162:165], v[190:193], v[100:103]
	v_mfma_f32_16x16x32_bf16 v[96:99], v[174:177], v[190:193], v[96:99]
	v_mfma_f32_16x16x32_bf16 v[84:87], v[162:165], v[198:201], v[84:87]
	v_mfma_f32_16x16x32_bf16 v[80:83], v[174:177], v[198:201], v[80:83]
	s_setprio 3
	s_barrier
	v_mfma_f32_16x16x32_bf16 v[68:71], v[162:165], v[206:209], v[68:71]
	v_mfma_f32_16x16x32_bf16 v[64:67], v[174:177], v[206:209], v[64:67]
	s_setprio 0
	s_add_i32 s0, s2, s40
	v_lshl_add_u64 v[210:211], s[26:27], 0, v[144:145]
	s_mov_b32 m0, s0
	ds_read_b128 v[178:181], v169 offset:16384
	ds_read_b128 v[182:185], v169 offset:17408
	ds_read_b128 v[186:189], v169 offset:18432
	ds_read_b128 v[190:193], v169 offset:19456
	ds_read_b128 v[194:197], v169 offset:20480
	ds_read_b128 v[198:201], v169 offset:21504
	ds_read_b128 v[202:205], v169 offset:22528
	ds_read_b128 v[206:209], v169 offset:23552
	global_load_lds_dwordx4 v[210:211], off
	s_add_i32 m0, s0, 0x2000
	s_add_u32 s0, s26, 0x40000
	v_lshl_add_u64 v[212:213], s[26:27], 0, v[152:153]
	s_addc_u32 s1, s27, 0
	s_add_i32 s2, s3, s40
	global_load_lds_dwordx4 v[212:213], off
	v_lshl_add_u64 v[214:215], s[0:1], 0, v[144:145]
	s_mov_b32 m0, s2
	v_lshl_add_u64 v[216:217], s[28:29], 0, v[150:151]
	global_load_lds_dwordx4 v[214:215], off
	v_lshl_add_u64 v[214:215], s[0:1], 0, v[152:153]
	s_add_i32 m0, s2, 0x2000
	s_nop 0
	global_load_lds_dwordx4 v[214:215], off
	v_lshl_add_u64 v[214:215], s[28:29], 0, v[148:149]
	s_mov_b32 m0, s41
	s_nop 0
	global_load_lds_dwordx4 v[214:215], off
	s_mov_b32 m0, s42
	s_nop 0
	global_load_lds_dwordx4 v[216:217], off
	s_waitcnt vmcnt(8)
	s_waitcnt lgkmcnt(0)
	s_barrier
; #define PG8_STAGE(bufoff, gbase, voff) do { _Pragma("unroll") for (int _i = 0; _i < 2; ++_i) \
;         __builtin_amdgcn_global_load_lds((const unsigned*)((const char*)(gbase) + (voff)[_i]), (PG8_LAS unsigned*)(lds + (bufoff) + ldsw + _i * 8192), 16, 0, 0); } while (0)
; #define PG8_LDA(dst, b, h) do { _Pragma("unroll") for (int m = 0; m < 4; ++m) _Pragma("unroll") for (int k = 0; k < 2; ++k) dst[m][k] = *(const PG8_LAS bf16x8*)(lds + PG8_SA(b, h) + aoff + m * 2048 + k * 1024); } while (0)
; #define PG8_LDB(dst, b, h) do { _Pragma("unroll") for (int n = 0; n < 2; ++n) _Pragma("unroll") for (int k = 0; k < 2; ++k) dst[n][k] = *(const PG8_LAS bf16x8*)(lds + PG8_SB(b, h) + boff + n * 2048 + k * 1024); } while (0)
; #define PG8_MMA(ai, bj, At, Bt) do { __builtin_amdgcn_s_setprio(1); _Pragma("unroll") for (int m = 0; m < 4; ++m) _Pragma("unroll") for (int n = 0; n < 2; ++n) _Pragma("unroll") for (int k = 0; k < 2; ++k) \
;         acc[ai][bj][m][n] = __builtin_amdgcn_mfma_f32_16x16x32_bf16(Bt[n][k], At[m][k], acc[ai][bj][m][n], 0, 0, 0); __builtin_amdgcn_s_setprio(0); } while (0)
; #define PG8_WAIT_V(n) asm volatile("s_waitcnt vmcnt(" #n ")" ::: "memory")
; #define PG8_WAIT_L(n) asm volatile("s_waitcnt lgkmcnt(" #n ")" ::: "memory")
; #define PG8_BAR __builtin_amdgcn_s_barrier()
; #define PG8_SCHED __builtin_amdgcn_sched_barrier(0)
; template <class Epi, class Sched, bool ALIGN_EPI = false, bool SP2 = false>
; __device__ __forceinline__ void gemm_phase(PG8_LAS unsigned char* lds, const Gemm g, const Sched& S, const Epi& E, int tid_in) {
;     ...
;             PG8_WAIT_V(8); PG8_WAIT_L(0); PG8_BAR; PG8_MMA(1, 0, At, B0); PG8_MMA(1, 1, At, B1); PG8_BAR; PG8_SCHED;
;             PG8_LDB(B0, 1, 0); PG8_LDB(B1, 1, 1); PG8_SCHED; PG8_LDA(At, 1, 0); PG8_STAGE(PG8_SA(0, 1), a2 + hstep, voffA);
;             PG8_WAIT_V(8); PG8_WAIT_L(0); PG8_BAR; PG8_MMA(0, 0, At, B0); PG8_MMA(0, 1, At, B1); PG8_BAR; PG8_SCHED;
	s_setprio 1
	s_waitcnt lgkmcnt(0)
	v_mfma_f32_16x16x32_bf16 v[60:63], v[128:131], v[178:181], v[60:63]
	v_mfma_f32_16x16x32_bf16 v[56:59], v[136:139], v[178:181], v[56:59]
	v_mfma_f32_16x16x32_bf16 v[44:47], v[128:131], v[186:189], v[44:47]
	v_mfma_f32_16x16x32_bf16 v[40:43], v[136:139], v[186:189], v[40:43]
	v_mfma_f32_16x16x32_bf16 v[28:31], v[128:131], v[194:197], v[28:31]
	v_mfma_f32_16x16x32_bf16 v[24:27], v[136:139], v[194:197], v[24:27]
	v_mfma_f32_16x16x32_bf16 v[12:15], v[128:131], v[202:205], v[12:15]
	v_mfma_f32_16x16x32_bf16 v[8:11], v[136:139], v[202:205], v[8:11]
	v_mfma_f32_16x16x32_bf16 v[60:63], v[132:135], v[182:185], v[60:63]
	v_mfma_f32_16x16x32_bf16 v[56:59], v[140:143], v[182:185], v[56:59]
	v_mfma_f32_16x16x32_bf16 v[44:47], v[132:135], v[190:193], v[44:47]
	v_mfma_f32_16x16x32_bf16 v[40:43], v[140:143], v[190:193], v[40:43]
	v_mfma_f32_16x16x32_bf16 v[28:31], v[132:135], v[198:201], v[28:31]
	v_mfma_f32_16x16x32_bf16 v[24:27], v[140:143], v[198:201], v[24:27]
	v_mfma_f32_16x16x32_bf16 v[12:15], v[132:135], v[206:209], v[12:15]
	v_mfma_f32_16x16x32_bf16 v[8:11], v[140:143], v[206:209], v[8:11]
	v_mfma_f32_16x16x32_bf16 v[52:55], v[158:161], v[178:181], v[52:55]
	v_mfma_f32_16x16x32_bf16 v[48:51], v[170:173], v[178:181], v[48:51]
	v_mfma_f32_16x16x32_bf16 v[36:39], v[158:161], v[186:189], v[36:39]
	v_mfma_f32_16x16x32_bf16 v[32:35], v[170:173], v[186:189], v[32:35]
	v_mfma_f32_16x16x32_bf16 v[20:23], v[158:161], v[194:197], v[20:23]
	v_mfma_f32_16x16x32_bf16 v[16:19], v[170:173], v[194:197], v[16:19]
	v_mfma_f32_16x16x32_bf16 v[4:7], v[158:161], v[202:205], v[4:7]
	v_mfma_f32_16x16x32_bf16 v[0:3], v[170:173], v[202:205], v[0:3]
	v_mfma_f32_16x16x32_bf16 v[52:55], v[162:165], v[182:185], v[52:55]
	v_mfma_f32_16x16x32_bf16 v[48:51], v[174:177], v[182:185], v[48:51]
	v_mfma_f32_16x16x32_bf16 v[36:39], v[162:165], v[190:193], v[36:39]
	v_mfma_f32_16x16x32_bf16 v[32:35], v[174:177], v[190:193], v[32:35]
	v_mfma_f32_16x16x32_bf16 v[20:23], v[162:165], v[198:201], v[20:23]
	v_mfma_f32_16x16x32_bf16 v[16:19], v[174:177], v[198:201], v[16:19]
	s_setprio 3
	s_barrier
	v_mfma_f32_16x16x32_bf16 v[4:7], v[162:165], v[206:209], v[4:7]
	v_mfma_f32_16x16x32_bf16 v[0:3], v[174:177], v[206:209], v[0:3]
	s_setprio 0
	s_add_i32 s2, 0, 0x18000
	s_add_i32 s3, 0, 0x1c000
	v_add_u32_e32 v140, s2, v168
	v_add_u32_e32 v174, s3, v168
	ds_read_b128 v[128:131], v140
	ds_read_b128 v[132:135], v140 offset:1024
	ds_read_b128 v[136:139], v140 offset:2048
	ds_read_b128 v[140:143], v140 offset:3072
	ds_read_b128 v[158:161], v174
	ds_read_b128 v[162:165], v174 offset:1024
	ds_read_b128 v[170:173], v174 offset:2048
	ds_read_b128 v[174:177], v174 offset:3072
	s_add_u32 s0, s28, 0x40000
	s_addc_u32 s1, s29, 0
	s_mov_b32 m0, s43
	v_lshl_add_u64 v[218:219], s[0:1], 0, v[148:149]
	ds_read_b128 v[178:181], v169 offset:32768
	ds_read_b128 v[182:185], v169 offset:33792
	ds_read_b128 v[186:189], v169 offset:34816
	ds_read_b128 v[190:193], v169 offset:35840
	ds_read_b128 v[194:197], v169 offset:36864
	ds_read_b128 v[198:201], v169 offset:37888
	ds_read_b128 v[202:205], v169 offset:38912
	ds_read_b128 v[206:209], v169 offset:39936
	global_load_lds_dwordx4 v[218:219], off
	v_lshl_add_u64 v[218:219], s[0:1], 0, v[150:151]
	s_mov_b32 m0, s44
	s_nop 0
	global_load_lds_dwordx4 v[218:219], off
	s_waitcnt vmcnt(8)
	s_waitcnt lgkmcnt(0)
	s_barrier
	s_setprio 1
	s_waitcnt lgkmcnt(0)
	v_mfma_f32_16x16x32_bf16 v[124:127], v[128:131], v[178:181], v[124:127]
	v_mfma_f32_16x16x32_bf16 v[120:123], v[136:139], v[178:181], v[120:123]
	v_mfma_f32_16x16x32_bf16 v[108:111], v[128:131], v[186:189], v[108:111]
	v_mfma_f32_16x16x32_bf16 v[104:107], v[136:139], v[186:189], v[104:107]
	v_mfma_f32_16x16x32_bf16 v[92:95], v[128:131], v[194:197], v[92:95]
	v_mfma_f32_16x16x32_bf16 v[88:91], v[136:139], v[194:197], v[88:91]
	v_mfma_f32_16x16x32_bf16 v[76:79], v[128:131], v[202:205], v[76:79]
	v_mfma_f32_16x16x32_bf16 v[72:75], v[136:139], v[202:205], v[72:75]
	v_mfma_f32_16x16x32_bf16 v[124:127], v[132:135], v[182:185], v[124:127]
	v_mfma_f32_16x16x32_bf16 v[120:123], v[140:143], v[182:185], v[120:123]
	v_mfma_f32_16x16x32_bf16 v[108:111], v[132:135], v[190:193], v[108:111]
	v_mfma_f32_16x16x32_bf16 v[104:107], v[140:143], v[190:193], v[104:107]
	v_mfma_f32_16x16x32_bf16 v[92:95], v[132:135], v[198:201], v[92:95]
	v_mfma_f32_16x16x32_bf16 v[88:91], v[140:143], v[198:201], v[88:91]
	v_mfma_f32_16x16x32_bf16 v[76:79], v[132:135], v[206:209], v[76:79]
	v_mfma_f32_16x16x32_bf16 v[72:75], v[140:143], v[206:209], v[72:75]
	v_mfma_f32_16x16x32_bf16 v[116:119], v[158:161], v[178:181], v[116:119]
	v_mfma_f32_16x16x32_bf16 v[112:115], v[170:173], v[178:181], v[112:115]
	v_mfma_f32_16x16x32_bf16 v[100:103], v[158:161], v[186:189], v[100:103]
	v_mfma_f32_16x16x32_bf16 v[96:99], v[170:173], v[186:189], v[96:99]
	v_mfma_f32_16x16x32_bf16 v[84:87], v[158:161], v[194:197], v[84:87]
	v_mfma_f32_16x16x32_bf16 v[80:83], v[170:173], v[194:197], v[80:83]
	v_mfma_f32_16x16x32_bf16 v[68:71], v[158:161], v[202:205], v[68:71]
	v_mfma_f32_16x16x32_bf16 v[64:67], v[170:173], v[202:205], v[64:67]
	v_mfma_f32_16x16x32_bf16 v[116:119], v[162:165], v[182:185], v[116:119]
	v_mfma_f32_16x16x32_bf16 v[112:115], v[174:177], v[182:185], v[112:115]
	v_mfma_f32_16x16x32_bf16 v[100:103], v[162:165], v[190:193], v[100:103]
	v_mfma_f32_16x16x32_bf16 v[96:99], v[174:177], v[190:193], v[96:99]
	v_mfma_f32_16x16x32_bf16 v[84:87], v[162:165], v[198:201], v[84:87]
	v_mfma_f32_16x16x32_bf16 v[80:83], v[174:177], v[198:201], v[80:83]
	s_setprio 3
	s_barrier
; #define PG8_STAGE(bufoff, gbase, voff) do { _Pragma("unroll") for (int _i = 0; _i < 2; ++_i) \
;         __builtin_amdgcn_global_load_lds((const unsigned*)((const char*)(gbase) + (voff)[_i]), (PG8_LAS unsigned*)(lds + (bufoff) + ldsw + _i * 8192), 16, 0, 0); } while (0)
; #define PG8_LDA(dst, b, h) do { _Pragma("unroll") for (int m = 0; m < 4; ++m) _Pragma("unroll") for (int k = 0; k < 2; ++k) dst[m][k] = *(const PG8_LAS bf16x8*)(lds + PG8_SA(b, h) + aoff + m * 2048 + k * 1024); } while (0)
; #define PG8_MMA(ai, bj, At, Bt) do { __builtin_amdgcn_s_setprio(1); _Pragma("unroll") for (int m = 0; m < 4; ++m) _Pragma("unroll") for (int n = 0; n < 2; ++n) _Pragma("unroll") for (int k = 0; k < 2; ++k) \
;         acc[ai][bj][m][n] = __builtin_amdgcn_mfma_f32_16x16x32_bf16(Bt[n][k], At[m][k], acc[ai][bj][m][n], 0, 0, 0); __builtin_amdgcn_s_setprio(0); } while (0)
; #define PG8_WAIT_V(n) asm volatile("s_waitcnt vmcnt(" #n ")" ::: "memory")
; #define PG8_WAIT_L(n) asm volatile("s_waitcnt lgkmcnt(" #n ")" ::: "memory")
; #define PG8_BAR __builtin_amdgcn_s_barrier()
; #define PG8_SCHED __builtin_amdgcn_sched_barrier(0)
; template <class Epi, class Sched, bool ALIGN_EPI = false, bool SP2 = false>
; __device__ __forceinline__ void gemm_phase(PG8_LAS unsigned char* lds, const Gemm g, const Sched& S, const Epi& E, int tid_in) {
;     ...
;             PG8_WAIT_V(8); PG8_WAIT_L(0); PG8_BAR; PG8_MMA(0, 0, At, B0); PG8_MMA(0, 1, At, B1); PG8_BAR; PG8_SCHED;
;             PG8_LDA(At, 1, 1); PG8_STAGE(PG8_SB(1, 0), b3, voffB); PG8_STAGE(PG8_SB(1, 1), b3 + hstep, voffB); PG8_STAGE(PG8_SA(1, 0), a3, voffA);
;             PG8_WAIT_V(8); PG8_WAIT_L(0); PG8_BAR; PG8_MMA(1, 0, At, B0); PG8_MMA(1, 1, At, B1); PG8_BAR; PG8_SCHED;
	v_mfma_f32_16x16x32_bf16 v[68:71], v[162:165], v[206:209], v[68:71]
	v_mfma_f32_16x16x32_bf16 v[64:67], v[174:177], v[206:209], v[64:67]
	s_setprio 0
	s_add_i32 s0, s2, s40
	v_lshl_add_u64 v[210:211], v[210:211], 0, s[68:69]
	s_mov_b32 m0, s0
	ds_read_b128 v[178:181], v169 offset:49152
	ds_read_b128 v[182:185], v169 offset:50176
	ds_read_b128 v[186:189], v169 offset:51200
	ds_read_b128 v[190:193], v169 offset:52224
	ds_read_b128 v[194:197], v169 offset:53248
	ds_read_b128 v[198:201], v169 offset:54272
	ds_read_b128 v[202:205], v169 offset:55296
	ds_read_b128 v[206:209], v169 offset:56320
	global_load_lds_dwordx4 v[210:211], off
	s_add_i32 m0, s0, 0x2000
	s_add_u32 s0, s26, 0x40080
	v_lshl_add_u64 v[210:211], v[212:213], 0, s[68:69]
	s_addc_u32 s1, s27, 0
	s_add_i32 s2, s3, s40
	global_load_lds_dwordx4 v[210:211], off
	v_lshl_add_u64 v[210:211], s[0:1], 0, v[144:145]
	s_mov_b32 m0, s2
	s_nop 0
	global_load_lds_dwordx4 v[210:211], off
	v_lshl_add_u64 v[210:211], s[0:1], 0, v[152:153]
	s_add_i32 m0, s2, 0x2000
	s_nop 0
	global_load_lds_dwordx4 v[210:211], off
	v_lshl_add_u64 v[210:211], v[214:215], 0, s[68:69]
	s_mov_b32 m0, s50
	s_nop 0
	global_load_lds_dwordx4 v[210:211], off
	v_lshl_add_u64 v[210:211], v[216:217], 0, s[68:69]
	s_mov_b32 m0, s51
	s_nop 0
	global_load_lds_dwordx4 v[210:211], off
	s_waitcnt vmcnt(8)
	s_waitcnt lgkmcnt(0)
	s_barrier
	s_setprio 1
	s_waitcnt lgkmcnt(0)
	v_mfma_f32_16x16x32_bf16 v[60:63], v[128:131], v[178:181], v[60:63]
	v_mfma_f32_16x16x32_bf16 v[56:59], v[136:139], v[178:181], v[56:59]
	v_mfma_f32_16x16x32_bf16 v[44:47], v[128:131], v[186:189], v[44:47]
	v_mfma_f32_16x16x32_bf16 v[40:43], v[136:139], v[186:189], v[40:43]
	v_mfma_f32_16x16x32_bf16 v[28:31], v[128:131], v[194:197], v[28:31]
	v_mfma_f32_16x16x32_bf16 v[24:27], v[136:139], v[194:197], v[24:27]
	v_mfma_f32_16x16x32_bf16 v[12:15], v[128:131], v[202:205], v[12:15]
	v_mfma_f32_16x16x32_bf16 v[8:11], v[136:139], v[202:205], v[8:11]
	v_mfma_f32_16x16x32_bf16 v[60:63], v[132:135], v[182:185], v[60:63]
	v_mfma_f32_16x16x32_bf16 v[56:59], v[140:143], v[182:185], v[56:59]
	v_mfma_f32_16x16x32_bf16 v[44:47], v[132:135], v[190:193], v[44:47]
	v_mfma_f32_16x16x32_bf16 v[40:43], v[140:143], v[190:193], v[40:43]
	v_mfma_f32_16x16x32_bf16 v[28:31], v[132:135], v[198:201], v[28:31]
	v_mfma_f32_16x16x32_bf16 v[24:27], v[140:143], v[198:201], v[24:27]
	v_mfma_f32_16x16x32_bf16 v[12:15], v[132:135], v[206:209], v[12:15]
	v_mfma_f32_16x16x32_bf16 v[8:11], v[140:143], v[206:209], v[8:11]
	v_mfma_f32_16x16x32_bf16 v[52:55], v[158:161], v[178:181], v[52:55]
	v_mfma_f32_16x16x32_bf16 v[48:51], v[170:173], v[178:181], v[48:51]
	v_mfma_f32_16x16x32_bf16 v[36:39], v[158:161], v[186:189], v[36:39]
	v_mfma_f32_16x16x32_bf16 v[32:35], v[170:173], v[186:189], v[32:35]
	v_mfma_f32_16x16x32_bf16 v[20:23], v[158:161], v[194:197], v[20:23]
	v_mfma_f32_16x16x32_bf16 v[16:19], v[170:173], v[194:197], v[16:19]
	v_mfma_f32_16x16x32_bf16 v[4:7], v[158:161], v[202:205], v[4:7]
	v_mfma_f32_16x16x32_bf16 v[0:3], v[170:173], v[202:205], v[0:3]
	v_mfma_f32_16x16x32_bf16 v[52:55], v[162:165], v[182:185], v[52:55]
	v_mfma_f32_16x16x32_bf16 v[48:51], v[174:177], v[182:185], v[48:51]
	v_mfma_f32_16x16x32_bf16 v[36:39], v[162:165], v[190:193], v[36:39]
	v_mfma_f32_16x16x32_bf16 v[32:35], v[174:177], v[190:193], v[32:35]
	v_mfma_f32_16x16x32_bf16 v[20:23], v[162:165], v[198:201], v[20:23]
	v_mfma_f32_16x16x32_bf16 v[16:19], v[174:177], v[198:201], v[16:19]
	s_setprio 3
	s_barrier
	v_mfma_f32_16x16x32_bf16 v[4:7], v[162:165], v[206:209], v[4:7]
	v_mfma_f32_16x16x32_bf16 v[0:3], v[174:177], v[206:209], v[0:3]
	s_setprio 0
	s_add_i32 s55, s55, 2
	s_add_u32 s24, s24, 0x100
	s_addc_u32 s25, s25, 0
	s_add_u32 s53, s53, 0x100
	s_addc_u32 s54, s54, 0
	s_cmp_gt_u32 s55, 13
	s_cbranch_scc0 .LBB0_219
	s_and_b64 vcc, exec, s[14:15]
	s_cbranch_vccz .LBB0_222
	s_barrier

; #define PG8_STAGE(bufoff, gbase, voff) do { _Pragma("unroll") for (int _i = 0; _i < 2; ++_i) \
;         __builtin_amdgcn_global_load_lds((const unsigned*)((const char*)(gbase) + (voff)[_i]), (PG8_LAS unsigned*)(lds + (bufoff) + ldsw + _i * 8192), 16, 0, 0); } while (0)
; #define PG8_LDA(dst, b, h) do { _Pragma("unroll") for (int m = 0; m < 4; ++m) _Pragma("unroll") for (int k = 0; k < 2; ++k) dst[m][k] = *(const PG8_LAS bf16x8*)(lds + PG8_SA(b, h) + aoff + m * 2048 + k * 1024); } while (0)
; #define PG8_LDB(dst, b, h) do { _Pragma("unroll") for (int n = 0; n < 2; ++n) _Pragma("unroll") for (int k = 0; k < 2; ++k) dst[n][k] = *(const PG8_LAS bf16x8*)(lds + PG8_SB(b, h) + boff + n * 2048 + k * 1024); } while (0)
; #define PG8_MMA(ai, bj, At, Bt) do { __builtin_amdgcn_s_setprio(1); _Pragma("unroll") for (int m = 0; m < 4; ++m) _Pragma("unroll") for (int n = 0; n < 2; ++n) _Pragma("unroll") for (int k = 0; k < 2; ++k) \
;         acc[ai][bj][m][n] = __builtin_amdgcn_mfma_f32_16x16x32_bf16(Bt[n][k], At[m][k], acc[ai][bj][m][n], 0, 0, 0); __builtin_amdgcn_s_setprio(0); } while (0)
; #define PG8_WAIT_V(n) asm volatile("s_waitcnt vmcnt(" #n ")" ::: "memory")
; #define PG8_WAIT_L(n) asm volatile("s_waitcnt lgkmcnt(" #n ")" ::: "memory")
; #define PG8_BAR __builtin_amdgcn_s_barrier()
; template <class Epi, class Sched, bool ALIGN_EPI = false, bool SP2 = false>
; __device__ __forceinline__ void gemm_phase(PG8_LAS unsigned char* lds, const Gemm g, const Sched& S, const Epi& E, int tid_in) {
;     ...
;         const int nt = cur.nk ? cur.nk : nt_all;
;         for (int t = 0; t < nt; t += 2) {
;             const bool last = (t == nt - 2);
;             const char* a1 = cA + (size_t)(t + 1) * kstep;
;             const char* a2 = last ? nA : cA + (size_t)(t + 2) * kstep; const char* b2 = last ? nB : cB + (size_t)(t + 2) * kstep;
;             const char* a3 = a2 + kstep; const char* b3 = b2 + kstep;
;             if (last && has_next) S.a_ready(nxt);
;             if constexpr (SP2) {
;             PG8_LDB(B0, 0, 0); PG8_LDB(B1, 0, 1); PG8_SCHED; PG8_LDA(At, 0, 0); PG8_STAGE(PG8_SA(1, 1), a1 + hstep, voffA);
;             PG8_WAIT_V(8); PG8_WAIT_L(0); PG8_BAR; PG8_MMA(0, 0, At, B0); PG8_MMA(0, 1, At, B1); PG8_BAR; PG8_SCHED;
;             PG8_LDA(At, 0, 1); PG8_STAGE(PG8_SB(0, 0), b2, voffB); PG8_STAGE(PG8_SB(0, 1), b2 + hstep, voffB); PG8_STAGE(PG8_SA(0, 0), a2, voffA);
.LBB0_307:
	s_add_i32 s1, s0, 2
	s_add_u32 s26, s24, 0x80
	s_addc_u32 s27, s25, 0
	s_add_i32 s33, 0, 0x10000
	s_cmp_eq_u32 s67, s0
	s_cselect_b32 s27, s19, s27
	s_cselect_b32 s26, s18, s26
	v_add_u32_e32 v143, s33, v232
	s_cselect_b32 s71, s21, s69
	s_cselect_b32 s70, s20, s68
	s_add_i32 s0, 0, 0x14000
	s_waitcnt lgkmcnt(0)
	ds_read_b128 v[128:131], v143
	ds_read_b128 v[132:135], v143 offset:1024
	ds_read_b128 v[154:157], v143 offset:2048
	ds_read_b128 v[158:161], v143 offset:3072
	v_add_u32_e32 v143, s0, v232
	ds_read_b128 v[162:165], v143
	ds_read_b128 v[166:169], v143 offset:1024
	ds_read_b128 v[170:173], v143 offset:2048
	ds_read_b128 v[174:177], v143 offset:3072
	v_lshl_add_u64 v[210:211], s[24:25], 0, v[150:151]
	s_add_i32 m0, s23, 0xc000
	ds_read_b128 v[178:181], v233
	ds_read_b128 v[182:185], v233 offset:1024
	ds_read_b128 v[186:189], v233 offset:2048
	ds_read_b128 v[190:193], v233 offset:3072
	ds_read_b128 v[194:197], v233 offset:4096
	ds_read_b128 v[198:201], v233 offset:5120
	ds_read_b128 v[202:205], v233 offset:6144
	ds_read_b128 v[206:209], v233 offset:7168
	global_load_lds_dwordx4 v[210:211], off
	v_lshl_add_u64 v[210:211], s[24:25], 0, v[152:153]
	s_add_i32 m0, s23, 0xe000
	s_nop 0
	global_load_lds_dwordx4 v[210:211], off
	s_waitcnt vmcnt(8)
	s_waitcnt lgkmcnt(0)
	s_barrier
	s_setprio 1
	s_waitcnt lgkmcnt(0)
	v_mfma_f32_16x16x32_bf16 v[124:127], v[128:131], v[178:181], v[124:127]
	v_mfma_f32_16x16x32_bf16 v[120:123], v[154:157], v[178:181], v[120:123]
	v_mfma_f32_16x16x32_bf16 v[116:119], v[128:131], v[186:189], v[116:119]
	v_mfma_f32_16x16x32_bf16 v[112:115], v[154:157], v[186:189], v[112:115]
	v_mfma_f32_16x16x32_bf16 v[108:111], v[128:131], v[194:197], v[108:111]
	v_mfma_f32_16x16x32_bf16 v[104:107], v[154:157], v[194:197], v[104:107]
	v_mfma_f32_16x16x32_bf16 v[100:103], v[128:131], v[202:205], v[100:103]
	v_mfma_f32_16x16x32_bf16 v[96:99], v[154:157], v[202:205], v[96:99]
	v_mfma_f32_16x16x32_bf16 v[124:127], v[132:135], v[182:185], v[124:127]
	v_mfma_f32_16x16x32_bf16 v[120:123], v[158:161], v[182:185], v[120:123]
	v_mfma_f32_16x16x32_bf16 v[116:119], v[132:135], v[190:193], v[116:119]
	v_mfma_f32_16x16x32_bf16 v[112:115], v[158:161], v[190:193], v[112:115]
	v_mfma_f32_16x16x32_bf16 v[108:111], v[132:135], v[198:201], v[108:111]
	v_mfma_f32_16x16x32_bf16 v[104:107], v[158:161], v[198:201], v[104:107]
	v_mfma_f32_16x16x32_bf16 v[100:103], v[132:135], v[206:209], v[100:103]
	v_mfma_f32_16x16x32_bf16 v[96:99], v[158:161], v[206:209], v[96:99]
	v_mfma_f32_16x16x32_bf16 v[60:63], v[162:165], v[178:181], v[60:63]
	v_mfma_f32_16x16x32_bf16 v[56:59], v[170:173], v[178:181], v[56:59]
	v_mfma_f32_16x16x32_bf16 v[52:55], v[162:165], v[186:189], v[52:55]
	v_mfma_f32_16x16x32_bf16 v[48:51], v[170:173], v[186:189], v[48:51]
	v_mfma_f32_16x16x32_bf16 v[44:47], v[162:165], v[194:197], v[44:47]
	v_mfma_f32_16x16x32_bf16 v[40:43], v[170:173], v[194:197], v[40:43]
	v_mfma_f32_16x16x32_bf16 v[36:39], v[162:165], v[202:205], v[36:39]
	v_mfma_f32_16x16x32_bf16 v[32:35], v[170:173], v[202:205], v[32:35]
	v_mfma_f32_16x16x32_bf16 v[60:63], v[166:169], v[182:185], v[60:63]
	v_mfma_f32_16x16x32_bf16 v[56:59], v[174:177], v[182:185], v[56:59]
	v_mfma_f32_16x16x32_bf16 v[52:55], v[166:169], v[190:193], v[52:55]
	v_mfma_f32_16x16x32_bf16 v[48:51], v[174:177], v[190:193], v[48:51]
	v_mfma_f32_16x16x32_bf16 v[44:47], v[166:169], v[198:201], v[44:47]
	v_mfma_f32_16x16x32_bf16 v[40:43], v[174:177], v[198:201], v[40:43]
	s_setprio 3
	s_barrier
	v_mfma_f32_16x16x32_bf16 v[36:39], v[166:169], v[206:209], v[36:39]
	v_mfma_f32_16x16x32_bf16 v[32:35], v[174:177], v[206:209], v[32:35]
	s_setprio 0
	s_add_i32 s33, s33, s31
	v_lshl_add_u64 v[210:211], s[70:71], 0, v[144:145]
	s_mov_b32 m0, s33
	ds_read_b128 v[178:181], v233 offset:16384
	ds_read_b128 v[182:185], v233 offset:17408
	ds_read_b128 v[186:189], v233 offset:18432
	ds_read_b128 v[190:193], v233 offset:19456
	ds_read_b128 v[194:197], v233 offset:20480
	ds_read_b128 v[198:201], v233 offset:21504
	ds_read_b128 v[202:205], v233 offset:22528
	ds_read_b128 v[206:209], v233 offset:23552
	global_load_lds_dwordx4 v[210:211], off
	s_add_i32 m0, s33, 0x2000
	v_lshl_add_u64 v[212:213], s[70:71], 0, v[140:141]
	s_add_u32 s70, s70, s90
	s_addc_u32 s71, s71, 0
	s_add_i32 s0, s0, s31
	global_load_lds_dwordx4 v[212:213], off
	v_lshl_add_u64 v[214:215], s[70:71], 0, v[144:145]
	s_mov_b32 m0, s0
	v_lshl_add_u64 v[216:217], s[70:71], 0, v[140:141]
	global_load_lds_dwordx4 v[214:215], off
	s_add_i32 m0, s0, 0x2000
	v_lshl_add_u64 v[218:219], s[26:27], 0, v[136:137]
	global_load_lds_dwordx4 v[216:217], off
	s_mov_b32 m0, s23
	v_lshl_add_u64 v[234:235], s[26:27], 0, v[138:139]
	global_load_lds_dwordx4 v[218:219], off
	s_mov_b32 m0, s41
	s_nop 0
	global_load_lds_dwordx4 v[234:235], off
	s_waitcnt vmcnt(8)
	s_waitcnt lgkmcnt(0)
	s_barrier
; #define PG8_STAGE(bufoff, gbase, voff) do { _Pragma("unroll") for (int _i = 0; _i < 2; ++_i) \
;         __builtin_amdgcn_global_load_lds((const unsigned*)((const char*)(gbase) + (voff)[_i]), (PG8_LAS unsigned*)(lds + (bufoff) + ldsw + _i * 8192), 16, 0, 0); } while (0)
; #define PG8_LDA(dst, b, h) do { _Pragma("unroll") for (int m = 0; m < 4; ++m) _Pragma("unroll") for (int k = 0; k < 2; ++k) dst[m][k] = *(const PG8_LAS bf16x8*)(lds + PG8_SA(b, h) + aoff + m * 2048 + k * 1024); } while (0)
; #define PG8_LDB(dst, b, h) do { _Pragma("unroll") for (int n = 0; n < 2; ++n) _Pragma("unroll") for (int k = 0; k < 2; ++k) dst[n][k] = *(const PG8_LAS bf16x8*)(lds + PG8_SB(b, h) + boff + n * 2048 + k * 1024); } while (0)
; #define PG8_MMA(ai, bj, At, Bt) do { __builtin_amdgcn_s_setprio(1); _Pragma("unroll") for (int m = 0; m < 4; ++m) _Pragma("unroll") for (int n = 0; n < 2; ++n) _Pragma("unroll") for (int k = 0; k < 2; ++k) \
;         acc[ai][bj][m][n] = __builtin_amdgcn_mfma_f32_16x16x32_bf16(Bt[n][k], At[m][k], acc[ai][bj][m][n], 0, 0, 0); __builtin_amdgcn_s_setprio(0); } while (0)
; #define PG8_WAIT_V(n) asm volatile("s_waitcnt vmcnt(" #n ")" ::: "memory")
; #define PG8_WAIT_L(n) asm volatile("s_waitcnt lgkmcnt(" #n ")" ::: "memory")
; #define PG8_BAR __builtin_amdgcn_s_barrier()
; #define PG8_SCHED __builtin_amdgcn_sched_barrier(0)
; template <class Epi, class Sched, bool ALIGN_EPI = false, bool SP2 = false>
; __device__ __forceinline__ void gemm_phase(PG8_LAS unsigned char* lds, const Gemm g, const Sched& S, const Epi& E, int tid_in) {
;     ...
;             PG8_WAIT_V(8); PG8_WAIT_L(0); PG8_BAR; PG8_MMA(1, 0, At, B0); PG8_MMA(1, 1, At, B1); PG8_BAR; PG8_SCHED;
;             PG8_LDB(B0, 1, 0); PG8_LDB(B1, 1, 1); PG8_SCHED; PG8_LDA(At, 1, 0); PG8_STAGE(PG8_SA(0, 1), a2 + hstep, voffA);
;             PG8_WAIT_V(8); PG8_WAIT_L(0); PG8_BAR; PG8_MMA(0, 0, At, B0); PG8_MMA(0, 1, At, B1); PG8_BAR; PG8_SCHED;
	s_setprio 1
	s_waitcnt lgkmcnt(0)
	v_mfma_f32_16x16x32_bf16 v[92:95], v[128:131], v[178:181], v[92:95]
	v_mfma_f32_16x16x32_bf16 v[88:91], v[154:157], v[178:181], v[88:91]
	v_mfma_f32_16x16x32_bf16 v[84:87], v[128:131], v[186:189], v[84:87]
	v_mfma_f32_16x16x32_bf16 v[80:83], v[154:157], v[186:189], v[80:83]
	v_mfma_f32_16x16x32_bf16 v[76:79], v[128:131], v[194:197], v[76:79]
	v_mfma_f32_16x16x32_bf16 v[72:75], v[154:157], v[194:197], v[72:75]
	v_mfma_f32_16x16x32_bf16 v[68:71], v[128:131], v[202:205], v[68:71]
	v_mfma_f32_16x16x32_bf16 v[64:67], v[154:157], v[202:205], v[64:67]
	v_mfma_f32_16x16x32_bf16 v[92:95], v[132:135], v[182:185], v[92:95]
	v_mfma_f32_16x16x32_bf16 v[88:91], v[158:161], v[182:185], v[88:91]
	v_mfma_f32_16x16x32_bf16 v[84:87], v[132:135], v[190:193], v[84:87]
	v_mfma_f32_16x16x32_bf16 v[80:83], v[158:161], v[190:193], v[80:83]
	v_mfma_f32_16x16x32_bf16 v[76:79], v[132:135], v[198:201], v[76:79]
	v_mfma_f32_16x16x32_bf16 v[72:75], v[158:161], v[198:201], v[72:75]
	v_mfma_f32_16x16x32_bf16 v[68:71], v[132:135], v[206:209], v[68:71]
	v_mfma_f32_16x16x32_bf16 v[64:67], v[158:161], v[206:209], v[64:67]
	v_mfma_f32_16x16x32_bf16 v[28:31], v[162:165], v[178:181], v[28:31]
	v_mfma_f32_16x16x32_bf16 v[24:27], v[170:173], v[178:181], v[24:27]
	v_mfma_f32_16x16x32_bf16 v[20:23], v[162:165], v[186:189], v[20:23]
	v_mfma_f32_16x16x32_bf16 v[16:19], v[170:173], v[186:189], v[16:19]
	v_mfma_f32_16x16x32_bf16 v[12:15], v[162:165], v[194:197], v[12:15]
	v_mfma_f32_16x16x32_bf16 v[8:11], v[170:173], v[194:197], v[8:11]
	v_mfma_f32_16x16x32_bf16 v[4:7], v[162:165], v[202:205], v[4:7]
	v_mfma_f32_16x16x32_bf16 v[0:3], v[170:173], v[202:205], v[0:3]
	v_mfma_f32_16x16x32_bf16 v[28:31], v[166:169], v[182:185], v[28:31]
	v_mfma_f32_16x16x32_bf16 v[24:27], v[174:177], v[182:185], v[24:27]
	v_mfma_f32_16x16x32_bf16 v[20:23], v[166:169], v[190:193], v[20:23]
	v_mfma_f32_16x16x32_bf16 v[16:19], v[174:177], v[190:193], v[16:19]
	v_mfma_f32_16x16x32_bf16 v[12:15], v[166:169], v[198:201], v[12:15]
	v_mfma_f32_16x16x32_bf16 v[8:11], v[174:177], v[198:201], v[8:11]
	s_setprio 3
	s_barrier
	v_mfma_f32_16x16x32_bf16 v[4:7], v[166:169], v[206:209], v[4:7]
	v_mfma_f32_16x16x32_bf16 v[0:3], v[174:177], v[206:209], v[0:3]
	s_setprio 0
	s_add_i32 s0, 0, 0x18000
	v_add_u32_e32 v143, s0, v232
	s_add_i32 s33, 0, 0x1c000
	ds_read_b128 v[128:131], v143
	ds_read_b128 v[132:135], v143 offset:1024
	ds_read_b128 v[154:157], v143 offset:2048
	ds_read_b128 v[158:161], v143 offset:3072
	v_add_u32_e32 v143, s33, v232
	ds_read_b128 v[162:165], v143
	ds_read_b128 v[166:169], v143 offset:1024
	ds_read_b128 v[170:173], v143 offset:2048
	ds_read_b128 v[174:177], v143 offset:3072
	s_add_u32 s26, s26, s90
	s_addc_u32 s27, s27, 0
	s_mov_b32 m0, s42
	v_lshl_add_u64 v[236:237], s[26:27], 0, v[136:137]
	ds_read_b128 v[178:181], v233 offset:32768
	ds_read_b128 v[182:185], v233 offset:33792
	ds_read_b128 v[186:189], v233 offset:34816
	ds_read_b128 v[190:193], v233 offset:35840
	ds_read_b128 v[194:197], v233 offset:36864
	ds_read_b128 v[198:201], v233 offset:37888
	ds_read_b128 v[202:205], v233 offset:38912
	ds_read_b128 v[206:209], v233 offset:39936
	global_load_lds_dwordx4 v[236:237], off
	v_lshl_add_u64 v[236:237], s[26:27], 0, v[138:139]
	s_mov_b32 m0, s43
	s_nop 0
	global_load_lds_dwordx4 v[236:237], off
	s_waitcnt vmcnt(8)
	s_waitcnt lgkmcnt(0)
	s_barrier
	s_setprio 1
	s_waitcnt lgkmcnt(0)
	v_mfma_f32_16x16x32_bf16 v[124:127], v[128:131], v[178:181], v[124:127]
	v_mfma_f32_16x16x32_bf16 v[120:123], v[154:157], v[178:181], v[120:123]
	v_mfma_f32_16x16x32_bf16 v[116:119], v[128:131], v[186:189], v[116:119]
	v_mfma_f32_16x16x32_bf16 v[112:115], v[154:157], v[186:189], v[112:115]
	v_mfma_f32_16x16x32_bf16 v[108:111], v[128:131], v[194:197], v[108:111]
	v_mfma_f32_16x16x32_bf16 v[104:107], v[154:157], v[194:197], v[104:107]
	v_mfma_f32_16x16x32_bf16 v[100:103], v[128:131], v[202:205], v[100:103]
	v_mfma_f32_16x16x32_bf16 v[96:99], v[154:157], v[202:205], v[96:99]
	v_mfma_f32_16x16x32_bf16 v[124:127], v[132:135], v[182:185], v[124:127]
	v_mfma_f32_16x16x32_bf16 v[120:123], v[158:161], v[182:185], v[120:123]
	v_mfma_f32_16x16x32_bf16 v[116:119], v[132:135], v[190:193], v[116:119]
	v_mfma_f32_16x16x32_bf16 v[112:115], v[158:161], v[190:193], v[112:115]
	v_mfma_f32_16x16x32_bf16 v[108:111], v[132:135], v[198:201], v[108:111]
	v_mfma_f32_16x16x32_bf16 v[104:107], v[158:161], v[198:201], v[104:107]
	v_mfma_f32_16x16x32_bf16 v[100:103], v[132:135], v[206:209], v[100:103]
	v_mfma_f32_16x16x32_bf16 v[96:99], v[158:161], v[206:209], v[96:99]
	v_mfma_f32_16x16x32_bf16 v[60:63], v[162:165], v[178:181], v[60:63]
	v_mfma_f32_16x16x32_bf16 v[56:59], v[170:173], v[178:181], v[56:59]
	v_mfma_f32_16x16x32_bf16 v[52:55], v[162:165], v[186:189], v[52:55]
	v_mfma_f32_16x16x32_bf16 v[48:51], v[170:173], v[186:189], v[48:51]
	v_mfma_f32_16x16x32_bf16 v[44:47], v[162:165], v[194:197], v[44:47]
	v_mfma_f32_16x16x32_bf16 v[40:43], v[170:173], v[194:197], v[40:43]
	v_mfma_f32_16x16x32_bf16 v[36:39], v[162:165], v[202:205], v[36:39]
	v_mfma_f32_16x16x32_bf16 v[32:35], v[170:173], v[202:205], v[32:35]
	v_mfma_f32_16x16x32_bf16 v[60:63], v[166:169], v[182:185], v[60:63]
	v_mfma_f32_16x16x32_bf16 v[56:59], v[174:177], v[182:185], v[56:59]
	v_mfma_f32_16x16x32_bf16 v[52:55], v[166:169], v[190:193], v[52:55]
	v_mfma_f32_16x16x32_bf16 v[48:51], v[174:177], v[190:193], v[48:51]
	v_mfma_f32_16x16x32_bf16 v[44:47], v[166:169], v[198:201], v[44:47]
	v_mfma_f32_16x16x32_bf16 v[40:43], v[174:177], v[198:201], v[40:43]
	s_setprio 3
	s_barrier
; #define PG8_STAGE(bufoff, gbase, voff) do { _Pragma("unroll") for (int _i = 0; _i < 2; ++_i) \
;         __builtin_amdgcn_global_load_lds((const unsigned*)((const char*)(gbase) + (voff)[_i]), (PG8_LAS unsigned*)(lds + (bufoff) + ldsw + _i * 8192), 16, 0, 0); } while (0)
; #define PG8_LDA(dst, b, h) do { _Pragma("unroll") for (int m = 0; m < 4; ++m) _Pragma("unroll") for (int k = 0; k < 2; ++k) dst[m][k] = *(const PG8_LAS bf16x8*)(lds + PG8_SA(b, h) + aoff + m * 2048 + k * 1024); } while (0)
; #define PG8_MMA(ai, bj, At, Bt) do { __builtin_amdgcn_s_setprio(1); _Pragma("unroll") for (int m = 0; m < 4; ++m) _Pragma("unroll") for (int n = 0; n < 2; ++n) _Pragma("unroll") for (int k = 0; k < 2; ++k) \
;         acc[ai][bj][m][n] = __builtin_amdgcn_mfma_f32_16x16x32_bf16(Bt[n][k], At[m][k], acc[ai][bj][m][n], 0, 0, 0); __builtin_amdgcn_s_setprio(0); } while (0)
; #define PG8_WAIT_V(n) asm volatile("s_waitcnt vmcnt(" #n ")" ::: "memory")
; #define PG8_WAIT_L(n) asm volatile("s_waitcnt lgkmcnt(" #n ")" ::: "memory")
; #define PG8_BAR __builtin_amdgcn_s_barrier()
; #define PG8_SCHED __builtin_amdgcn_sched_barrier(0)
; template <class Epi, class Sched, bool ALIGN_EPI = false, bool SP2 = false>
; __device__ __forceinline__ void gemm_phase(PG8_LAS unsigned char* lds, const Gemm g, const Sched& S, const Epi& E, int tid_in) {
;     ...
;             PG8_WAIT_V(8); PG8_WAIT_L(0); PG8_BAR; PG8_MMA(0, 0, At, B0); PG8_MMA(0, 1, At, B1); PG8_BAR; PG8_SCHED;
;             PG8_LDA(At, 1, 1); PG8_STAGE(PG8_SB(1, 0), b3, voffB); PG8_STAGE(PG8_SB(1, 1), b3 + hstep, voffB); PG8_STAGE(PG8_SA(1, 0), a3, voffA);
;             PG8_WAIT_V(8); PG8_WAIT_L(0); PG8_BAR; PG8_MMA(1, 0, At, B0); PG8_MMA(1, 1, At, B1); PG8_BAR; PG8_SCHED;
	v_mfma_f32_16x16x32_bf16 v[36:39], v[166:169], v[206:209], v[36:39]
	v_mfma_f32_16x16x32_bf16 v[32:35], v[174:177], v[206:209], v[32:35]
	s_setprio 0
	s_add_i32 s0, s0, s31
	v_lshl_add_u64 v[210:211], v[210:211], 0, vcc
	s_mov_b32 m0, s0
	ds_read_b128 v[178:181], v233 offset:49152
	ds_read_b128 v[182:185], v233 offset:50176
	ds_read_b128 v[186:189], v233 offset:51200
	ds_read_b128 v[190:193], v233 offset:52224
	ds_read_b128 v[194:197], v233 offset:53248
	ds_read_b128 v[198:201], v233 offset:54272
	ds_read_b128 v[202:205], v233 offset:55296
	ds_read_b128 v[206:209], v233 offset:56320
	global_load_lds_dwordx4 v[210:211], off
	v_lshl_add_u64 v[210:211], v[212:213], 0, vcc
	s_add_i32 m0, s0, 0x2000
	s_add_i32 s0, s33, s31
	global_load_lds_dwordx4 v[210:211], off
	v_lshl_add_u64 v[210:211], v[214:215], 0, vcc
	s_mov_b32 m0, s0
	s_nop 0
	global_load_lds_dwordx4 v[210:211], off
	v_lshl_add_u64 v[210:211], v[216:217], 0, vcc
	s_add_i32 m0, s0, 0x2000
	s_nop 0
	global_load_lds_dwordx4 v[210:211], off
	v_lshl_add_u64 v[210:211], v[218:219], 0, vcc
	s_mov_b32 m0, s53
	s_nop 0
	global_load_lds_dwordx4 v[210:211], off
	v_lshl_add_u64 v[210:211], v[234:235], 0, vcc
	s_mov_b32 m0, s54
	s_nop 0
	global_load_lds_dwordx4 v[210:211], off
	s_waitcnt vmcnt(8)
	s_waitcnt lgkmcnt(0)
	s_barrier
	s_setprio 1
	s_waitcnt lgkmcnt(0)
	v_mfma_f32_16x16x32_bf16 v[92:95], v[128:131], v[178:181], v[92:95]
	v_mfma_f32_16x16x32_bf16 v[88:91], v[154:157], v[178:181], v[88:91]
	v_mfma_f32_16x16x32_bf16 v[84:87], v[128:131], v[186:189], v[84:87]
	v_mfma_f32_16x16x32_bf16 v[80:83], v[154:157], v[186:189], v[80:83]
	v_mfma_f32_16x16x32_bf16 v[76:79], v[128:131], v[194:197], v[76:79]
	v_mfma_f32_16x16x32_bf16 v[72:75], v[154:157], v[194:197], v[72:75]
	v_mfma_f32_16x16x32_bf16 v[68:71], v[128:131], v[202:205], v[68:71]
	v_mfma_f32_16x16x32_bf16 v[64:67], v[154:157], v[202:205], v[64:67]
	v_mfma_f32_16x16x32_bf16 v[92:95], v[132:135], v[182:185], v[92:95]
	v_mfma_f32_16x16x32_bf16 v[88:91], v[158:161], v[182:185], v[88:91]
	v_mfma_f32_16x16x32_bf16 v[84:87], v[132:135], v[190:193], v[84:87]
	v_mfma_f32_16x16x32_bf16 v[80:83], v[158:161], v[190:193], v[80:83]
	v_mfma_f32_16x16x32_bf16 v[76:79], v[132:135], v[198:201], v[76:79]
	v_mfma_f32_16x16x32_bf16 v[72:75], v[158:161], v[198:201], v[72:75]
	v_mfma_f32_16x16x32_bf16 v[68:71], v[132:135], v[206:209], v[68:71]
	v_mfma_f32_16x16x32_bf16 v[64:67], v[158:161], v[206:209], v[64:67]
	v_mfma_f32_16x16x32_bf16 v[28:31], v[162:165], v[178:181], v[28:31]
	v_mfma_f32_16x16x32_bf16 v[24:27], v[170:173], v[178:181], v[24:27]
	v_mfma_f32_16x16x32_bf16 v[20:23], v[162:165], v[186:189], v[20:23]
	v_mfma_f32_16x16x32_bf16 v[16:19], v[170:173], v[186:189], v[16:19]
	v_mfma_f32_16x16x32_bf16 v[12:15], v[162:165], v[194:197], v[12:15]
	v_mfma_f32_16x16x32_bf16 v[8:11], v[170:173], v[194:197], v[8:11]
	v_mfma_f32_16x16x32_bf16 v[4:7], v[162:165], v[202:205], v[4:7]
	v_mfma_f32_16x16x32_bf16 v[0:3], v[170:173], v[202:205], v[0:3]
	v_mfma_f32_16x16x32_bf16 v[28:31], v[166:169], v[182:185], v[28:31]
	v_mfma_f32_16x16x32_bf16 v[24:27], v[174:177], v[182:185], v[24:27]
	v_mfma_f32_16x16x32_bf16 v[20:23], v[166:169], v[190:193], v[20:23]
	v_mfma_f32_16x16x32_bf16 v[16:19], v[174:177], v[190:193], v[16:19]
	v_mfma_f32_16x16x32_bf16 v[12:15], v[166:169], v[198:201], v[12:15]
	v_mfma_f32_16x16x32_bf16 v[8:11], v[174:177], v[198:201], v[8:11]
	s_setprio 3
	s_barrier
	v_mfma_f32_16x16x32_bf16 v[4:7], v[166:169], v[206:209], v[4:7]
	v_mfma_f32_16x16x32_bf16 v[0:3], v[174:177], v[206:209], v[0:3]
	s_setprio 0
	s_add_u32 s24, s24, 0x100
	s_addc_u32 s25, s25, 0
	s_add_u32 s68, s68, 0x100
	s_addc_u32 s69, s69, 0
	s_cmp_ge_i32 s1, s17
	s_mov_b32 s0, s1
	s_cbranch_scc0 .LBB0_307
	v_readlane_b32 s70, v253, 53
	s_mov_b64 s[68:69], 0x80
	v_readlane_b32 s71, v253, 54
	s_and_b64 vcc, exec, s[12:13]
	s_cbranch_vccz .LBB0_310

; #define PG8_STAGE(bufoff, gbase, voff) do { _Pragma("unroll") for (int _i = 0; _i < 2; ++_i) \
;         __builtin_amdgcn_global_load_lds((const unsigned*)((const char*)(gbase) + (voff)[_i]), (PG8_LAS unsigned*)(lds + (bufoff) + ldsw + _i * 8192), 16, 0, 0); } while (0)
; #define PG8_LDA(dst, b, h) do { _Pragma("unroll") for (int m = 0; m < 4; ++m) _Pragma("unroll") for (int k = 0; k < 2; ++k) dst[m][k] = *(const PG8_LAS bf16x8*)(lds + PG8_SA(b, h) + aoff + m * 2048 + k * 1024); } while (0)
; #define PG8_LDB(dst, b, h) do { _Pragma("unroll") for (int n = 0; n < 2; ++n) _Pragma("unroll") for (int k = 0; k < 2; ++k) dst[n][k] = *(const PG8_LAS bf16x8*)(lds + PG8_SB(b, h) + boff + n * 2048 + k * 1024); } while (0)
; #define PG8_MMA(ai, bj, At, Bt) do { __builtin_amdgcn_s_setprio(1); _Pragma("unroll") for (int m = 0; m < 4; ++m) _Pragma("unroll") for (int n = 0; n < 2; ++n) _Pragma("unroll") for (int k = 0; k < 2; ++k) \
;         acc[ai][bj][m][n] = __builtin_amdgcn_mfma_f32_16x16x32_bf16(Bt[n][k], At[m][k], acc[ai][bj][m][n], 0, 0, 0); __builtin_amdgcn_s_setprio(0); } while (0)
; #define PG8_WAIT_V(n) asm volatile("s_waitcnt vmcnt(" #n ")" ::: "memory")
; #define PG8_WAIT_L(n) asm volatile("s_waitcnt lgkmcnt(" #n ")" ::: "memory")
; #define PG8_BAR __builtin_amdgcn_s_barrier()
; #define PG8_SCHED __builtin_amdgcn_sched_barrier(0)
; template <class Epi, class Sched, bool ALIGN_EPI = false, bool SP2 = false>
; __device__ __forceinline__ void gemm_phase(PG8_LAS unsigned char* lds, const Gemm g, const Sched& S, const Epi& E, int tid_in) {
;     ...
;         for (int t = 0; t < nt; t += 2) {
;             const bool last = (t == nt - 2);
;             const char* a1 = cA + (size_t)(t + 1) * kstep;
;             const char* a2 = last ? nA : cA + (size_t)(t + 2) * kstep; const char* b2 = last ? nB : cB + (size_t)(t + 2) * kstep;
;             const char* a3 = a2 + kstep; const char* b3 = b2 + kstep;
;             if (last && has_next) S.a_ready(nxt);
;             if constexpr (SP2) {
;             PG8_LDB(B0, 0, 0); PG8_LDB(B1, 0, 1); PG8_SCHED; PG8_LDA(At, 0, 0); PG8_STAGE(PG8_SA(1, 1), a1 + hstep, voffA);
;             PG8_WAIT_V(8); PG8_WAIT_L(0); PG8_BAR; PG8_MMA(0, 0, At, B0); PG8_MMA(0, 1, At, B1); PG8_BAR; PG8_SCHED;
;             PG8_LDA(At, 0, 1); PG8_STAGE(PG8_SB(0, 0), b2, voffB); PG8_STAGE(PG8_SB(0, 1), b2 + hstep, voffB); PG8_STAGE(PG8_SA(0, 0), a2, voffA);
.LBB0_351:
	s_add_u32 s2, s20, 0xfffc0080
	s_addc_u32 s3, s21, -1
	s_add_i32 s33, 0, 0x10000
	s_cmp_eq_u32 s49, 12
	s_cselect_b32 s25, s11, s3
	s_cselect_b32 s24, s44, s2
	s_cselect_b32 s23, s9, s48
	s_cselect_b32 s22, s45, s47
	s_add_i32 s34, 0, 0x14000
	v_add_u32_e32 v60, s33, v164
	v_add_u32_e32 v174, s34, v164
	ds_read_b128 v[48:51], v60
	ds_read_b128 v[52:55], v60 offset:1024
	ds_read_b128 v[56:59], v60 offset:2048
	ds_read_b128 v[60:63], v60 offset:3072
	ds_read_b128 v[158:161], v174
	ds_read_b128 v[166:169], v174 offset:1024
	ds_read_b128 v[170:173], v174 offset:2048
	ds_read_b128 v[174:177], v174 offset:3072
	v_lshl_add_u64 v[210:211], s[20:21], 0, v[154:155]
	s_add_i32 m0, s19, 0xc000
	ds_read_b128 v[178:181], v165
	ds_read_b128 v[182:185], v165 offset:1024
	ds_read_b128 v[186:189], v165 offset:2048
	ds_read_b128 v[190:193], v165 offset:3072
	ds_read_b128 v[194:197], v165 offset:4096
	ds_read_b128 v[198:201], v165 offset:5120
	ds_read_b128 v[202:205], v165 offset:6144
	ds_read_b128 v[206:209], v165 offset:7168
	global_load_lds_dwordx4 v[210:211], off
	v_lshl_add_u64 v[210:211], s[20:21], 0, v[156:157]
	s_add_i32 m0, s19, 0xe000
	s_nop 0
	global_load_lds_dwordx4 v[210:211], off
	s_waitcnt vmcnt(8)
	s_waitcnt lgkmcnt(0)
	s_barrier
	s_setprio 1
	s_waitcnt lgkmcnt(0)
	v_mfma_f32_16x16x32_bf16 v[140:143], v[48:51], v[178:181], v[140:143]
	v_mfma_f32_16x16x32_bf16 v[136:139], v[56:59], v[178:181], v[136:139]
	v_mfma_f32_16x16x32_bf16 v[124:127], v[48:51], v[186:189], v[124:127]
	v_mfma_f32_16x16x32_bf16 v[120:123], v[56:59], v[186:189], v[120:123]
	v_mfma_f32_16x16x32_bf16 v[108:111], v[48:51], v[194:197], v[108:111]
	v_mfma_f32_16x16x32_bf16 v[104:107], v[56:59], v[194:197], v[104:107]
	v_mfma_f32_16x16x32_bf16 v[92:95], v[48:51], v[202:205], v[92:95]
	v_mfma_f32_16x16x32_bf16 v[88:91], v[56:59], v[202:205], v[88:91]
	v_mfma_f32_16x16x32_bf16 v[140:143], v[52:55], v[182:185], v[140:143]
	v_mfma_f32_16x16x32_bf16 v[136:139], v[60:63], v[182:185], v[136:139]
	v_mfma_f32_16x16x32_bf16 v[124:127], v[52:55], v[190:193], v[124:127]
	v_mfma_f32_16x16x32_bf16 v[120:123], v[60:63], v[190:193], v[120:123]
	v_mfma_f32_16x16x32_bf16 v[108:111], v[52:55], v[198:201], v[108:111]
	v_mfma_f32_16x16x32_bf16 v[104:107], v[60:63], v[198:201], v[104:107]
	v_mfma_f32_16x16x32_bf16 v[92:95], v[52:55], v[206:209], v[92:95]
	v_mfma_f32_16x16x32_bf16 v[88:91], v[60:63], v[206:209], v[88:91]
	v_mfma_f32_16x16x32_bf16 v[132:135], v[158:161], v[178:181], v[132:135]
	v_mfma_f32_16x16x32_bf16 v[128:131], v[170:173], v[178:181], v[128:131]
	v_mfma_f32_16x16x32_bf16 v[116:119], v[158:161], v[186:189], v[116:119]
	v_mfma_f32_16x16x32_bf16 v[112:115], v[170:173], v[186:189], v[112:115]
	v_mfma_f32_16x16x32_bf16 v[100:103], v[158:161], v[194:197], v[100:103]
	v_mfma_f32_16x16x32_bf16 v[96:99], v[170:173], v[194:197], v[96:99]
	v_mfma_f32_16x16x32_bf16 v[84:87], v[158:161], v[202:205], v[84:87]
	v_mfma_f32_16x16x32_bf16 v[80:83], v[170:173], v[202:205], v[80:83]
	v_mfma_f32_16x16x32_bf16 v[132:135], v[166:169], v[182:185], v[132:135]
	v_mfma_f32_16x16x32_bf16 v[128:131], v[174:177], v[182:185], v[128:131]
	v_mfma_f32_16x16x32_bf16 v[116:119], v[166:169], v[190:193], v[116:119]
	v_mfma_f32_16x16x32_bf16 v[112:115], v[174:177], v[190:193], v[112:115]
	v_mfma_f32_16x16x32_bf16 v[100:103], v[166:169], v[198:201], v[100:103]
	v_mfma_f32_16x16x32_bf16 v[96:99], v[174:177], v[198:201], v[96:99]
	s_setprio 3
	s_barrier
	v_mfma_f32_16x16x32_bf16 v[84:87], v[166:169], v[206:209], v[84:87]
	v_mfma_f32_16x16x32_bf16 v[80:83], v[174:177], v[206:209], v[80:83]
	s_setprio 0
	s_add_i32 s2, s33, s35
	v_lshl_add_u64 v[210:211], s[22:23], 0, v[144:145]
	s_mov_b32 m0, s2
	ds_read_b128 v[178:181], v165 offset:16384
	ds_read_b128 v[182:185], v165 offset:17408
	ds_read_b128 v[186:189], v165 offset:18432
	ds_read_b128 v[190:193], v165 offset:19456
	ds_read_b128 v[194:197], v165 offset:20480
	ds_read_b128 v[198:201], v165 offset:21504
	ds_read_b128 v[202:205], v165 offset:22528
	ds_read_b128 v[206:209], v165 offset:23552
	global_load_lds_dwordx4 v[210:211], off
	s_add_i32 m0, s2, 0x2000
	s_add_u32 s2, s22, 0x40000
	v_lshl_add_u64 v[212:213], s[22:23], 0, v[148:149]
	s_addc_u32 s3, s23, 0
	s_add_i32 s33, s34, s35
	global_load_lds_dwordx4 v[212:213], off
	v_lshl_add_u64 v[214:215], s[2:3], 0, v[144:145]
	s_mov_b32 m0, s33
	v_lshl_add_u64 v[216:217], s[24:25], 0, v[150:151]
	global_load_lds_dwordx4 v[214:215], off
	v_lshl_add_u64 v[214:215], s[2:3], 0, v[148:149]
	s_add_i32 m0, s33, 0x2000
	s_nop 0
	global_load_lds_dwordx4 v[214:215], off
	v_lshl_add_u64 v[214:215], s[24:25], 0, v[152:153]
	s_mov_b32 m0, s19
	s_nop 0
	global_load_lds_dwordx4 v[214:215], off
	s_mov_b32 m0, s36
	s_nop 0
	global_load_lds_dwordx4 v[216:217], off
	s_waitcnt vmcnt(8)
	s_waitcnt lgkmcnt(0)
	s_barrier
; #define PG8_STAGE(bufoff, gbase, voff) do { _Pragma("unroll") for (int _i = 0; _i < 2; ++_i) \
;         __builtin_amdgcn_global_load_lds((const unsigned*)((const char*)(gbase) + (voff)[_i]), (PG8_LAS unsigned*)(lds + (bufoff) + ldsw + _i * 8192), 16, 0, 0); } while (0)
; #define PG8_LDA(dst, b, h) do { _Pragma("unroll") for (int m = 0; m < 4; ++m) _Pragma("unroll") for (int k = 0; k < 2; ++k) dst[m][k] = *(const PG8_LAS bf16x8*)(lds + PG8_SA(b, h) + aoff + m * 2048 + k * 1024); } while (0)
; #define PG8_LDB(dst, b, h) do { _Pragma("unroll") for (int n = 0; n < 2; ++n) _Pragma("unroll") for (int k = 0; k < 2; ++k) dst[n][k] = *(const PG8_LAS bf16x8*)(lds + PG8_SB(b, h) + boff + n * 2048 + k * 1024); } while (0)
; #define PG8_MMA(ai, bj, At, Bt) do { __builtin_amdgcn_s_setprio(1); _Pragma("unroll") for (int m = 0; m < 4; ++m) _Pragma("unroll") for (int n = 0; n < 2; ++n) _Pragma("unroll") for (int k = 0; k < 2; ++k) \
;         acc[ai][bj][m][n] = __builtin_amdgcn_mfma_f32_16x16x32_bf16(Bt[n][k], At[m][k], acc[ai][bj][m][n], 0, 0, 0); __builtin_amdgcn_s_setprio(0); } while (0)
; #define PG8_WAIT_V(n) asm volatile("s_waitcnt vmcnt(" #n ")" ::: "memory")
; #define PG8_WAIT_L(n) asm volatile("s_waitcnt lgkmcnt(" #n ")" ::: "memory")
; #define PG8_BAR __builtin_amdgcn_s_barrier()
; #define PG8_SCHED __builtin_amdgcn_sched_barrier(0)
; template <class Epi, class Sched, bool ALIGN_EPI = false, bool SP2 = false>
; __device__ __forceinline__ void gemm_phase(PG8_LAS unsigned char* lds, const Gemm g, const Sched& S, const Epi& E, int tid_in) {
;     ...
;             PG8_WAIT_V(8); PG8_WAIT_L(0); PG8_BAR; PG8_MMA(1, 0, At, B0); PG8_MMA(1, 1, At, B1); PG8_BAR; PG8_SCHED;
;             PG8_LDB(B0, 1, 0); PG8_LDB(B1, 1, 1); PG8_SCHED; PG8_LDA(At, 1, 0); PG8_STAGE(PG8_SA(0, 1), a2 + hstep, voffA);
;             PG8_WAIT_V(8); PG8_WAIT_L(0); PG8_BAR; PG8_MMA(0, 0, At, B0); PG8_MMA(0, 1, At, B1); PG8_BAR; PG8_SCHED;
	s_setprio 1
	s_waitcnt lgkmcnt(0)
	v_mfma_f32_16x16x32_bf16 v[76:79], v[48:51], v[178:181], v[76:79]
	v_mfma_f32_16x16x32_bf16 v[72:75], v[56:59], v[178:181], v[72:75]
	v_mfma_f32_16x16x32_bf16 v[44:47], v[48:51], v[186:189], v[44:47]
	v_mfma_f32_16x16x32_bf16 v[40:43], v[56:59], v[186:189], v[40:43]
	v_mfma_f32_16x16x32_bf16 v[28:31], v[48:51], v[194:197], v[28:31]
	v_mfma_f32_16x16x32_bf16 v[24:27], v[56:59], v[194:197], v[24:27]
	v_mfma_f32_16x16x32_bf16 v[12:15], v[48:51], v[202:205], v[12:15]
	v_mfma_f32_16x16x32_bf16 v[8:11], v[56:59], v[202:205], v[8:11]
	v_mfma_f32_16x16x32_bf16 v[76:79], v[52:55], v[182:185], v[76:79]
	v_mfma_f32_16x16x32_bf16 v[72:75], v[60:63], v[182:185], v[72:75]
	v_mfma_f32_16x16x32_bf16 v[44:47], v[52:55], v[190:193], v[44:47]
	v_mfma_f32_16x16x32_bf16 v[40:43], v[60:63], v[190:193], v[40:43]
	v_mfma_f32_16x16x32_bf16 v[28:31], v[52:55], v[198:201], v[28:31]
	v_mfma_f32_16x16x32_bf16 v[24:27], v[60:63], v[198:201], v[24:27]
	v_mfma_f32_16x16x32_bf16 v[12:15], v[52:55], v[206:209], v[12:15]
	v_mfma_f32_16x16x32_bf16 v[8:11], v[60:63], v[206:209], v[8:11]
	v_mfma_f32_16x16x32_bf16 v[36:39], v[158:161], v[186:189], v[36:39]
	v_mfma_f32_16x16x32_bf16 v[32:35], v[170:173], v[186:189], v[32:35]
	v_mfma_f32_16x16x32_bf16 v[20:23], v[158:161], v[194:197], v[20:23]
	v_mfma_f32_16x16x32_bf16 v[16:19], v[170:173], v[194:197], v[16:19]
	v_mfma_f32_16x16x32_bf16 v[4:7], v[158:161], v[202:205], v[4:7]
	v_mfma_f32_16x16x32_bf16 v[0:3], v[170:173], v[202:205], v[0:3]
	v_mfma_f32_16x16x32_bf16 v[48:51], v[158:161], v[178:181], v[68:71]
	v_mfma_f32_16x16x32_bf16 v[52:55], v[170:173], v[178:181], v[64:67]
	v_mfma_f32_16x16x32_bf16 v[36:39], v[166:169], v[190:193], v[36:39]
	v_mfma_f32_16x16x32_bf16 v[32:35], v[174:177], v[190:193], v[32:35]
	v_mfma_f32_16x16x32_bf16 v[20:23], v[166:169], v[198:201], v[20:23]
	v_mfma_f32_16x16x32_bf16 v[16:19], v[174:177], v[198:201], v[16:19]
	v_mfma_f32_16x16x32_bf16 v[4:7], v[166:169], v[206:209], v[4:7]
	v_mfma_f32_16x16x32_bf16 v[0:3], v[174:177], v[206:209], v[0:3]
	s_setprio 3
	s_barrier
	v_mfma_f32_16x16x32_bf16 v[48:51], v[166:169], v[182:185], v[48:51]
	v_mfma_f32_16x16x32_bf16 v[52:55], v[174:177], v[182:185], v[52:55]
	s_setprio 0
	s_add_i32 s33, 0, 0x18000
	s_add_i32 s34, 0, 0x1c000
	v_add_u32_e32 v68, s33, v164
	v_add_u32_e32 v174, s34, v164
	ds_read_b128 v[56:59], v68
	ds_read_b128 v[60:63], v68 offset:1024
	ds_read_b128 v[64:67], v68 offset:2048
	ds_read_b128 v[68:71], v68 offset:3072
	ds_read_b128 v[158:161], v174
	ds_read_b128 v[166:169], v174 offset:1024
	ds_read_b128 v[170:173], v174 offset:2048
	ds_read_b128 v[174:177], v174 offset:3072
	s_add_u32 s2, s24, 0x40000
	s_addc_u32 s3, s25, 0
	s_mov_b32 m0, s37
	v_lshl_add_u64 v[218:219], s[2:3], 0, v[152:153]
	ds_read_b128 v[178:181], v165 offset:32768
	ds_read_b128 v[182:185], v165 offset:33792
	ds_read_b128 v[186:189], v165 offset:34816
	ds_read_b128 v[190:193], v165 offset:35840
	ds_read_b128 v[194:197], v165 offset:36864
	ds_read_b128 v[198:201], v165 offset:37888
	ds_read_b128 v[202:205], v165 offset:38912
	ds_read_b128 v[206:209], v165 offset:39936
	global_load_lds_dwordx4 v[218:219], off
	v_lshl_add_u64 v[218:219], s[2:3], 0, v[150:151]
	s_mov_b32 m0, s38
	s_nop 0
	global_load_lds_dwordx4 v[218:219], off
	s_waitcnt vmcnt(8)
	s_waitcnt lgkmcnt(0)
	s_barrier
	s_setprio 1
	s_waitcnt lgkmcnt(0)
	v_mfma_f32_16x16x32_bf16 v[140:143], v[56:59], v[178:181], v[140:143]
	v_mfma_f32_16x16x32_bf16 v[136:139], v[64:67], v[178:181], v[136:139]
	v_mfma_f32_16x16x32_bf16 v[124:127], v[56:59], v[186:189], v[124:127]
	v_mfma_f32_16x16x32_bf16 v[120:123], v[64:67], v[186:189], v[120:123]
	v_mfma_f32_16x16x32_bf16 v[108:111], v[56:59], v[194:197], v[108:111]
	v_mfma_f32_16x16x32_bf16 v[104:107], v[64:67], v[194:197], v[104:107]
	v_mfma_f32_16x16x32_bf16 v[92:95], v[56:59], v[202:205], v[92:95]
	v_mfma_f32_16x16x32_bf16 v[88:91], v[64:67], v[202:205], v[88:91]
	v_mfma_f32_16x16x32_bf16 v[140:143], v[60:63], v[182:185], v[140:143]
	v_mfma_f32_16x16x32_bf16 v[136:139], v[68:71], v[182:185], v[136:139]
	v_mfma_f32_16x16x32_bf16 v[124:127], v[60:63], v[190:193], v[124:127]
	v_mfma_f32_16x16x32_bf16 v[120:123], v[68:71], v[190:193], v[120:123]
	v_mfma_f32_16x16x32_bf16 v[108:111], v[60:63], v[198:201], v[108:111]
	v_mfma_f32_16x16x32_bf16 v[104:107], v[68:71], v[198:201], v[104:107]
	v_mfma_f32_16x16x32_bf16 v[92:95], v[60:63], v[206:209], v[92:95]
	v_mfma_f32_16x16x32_bf16 v[88:91], v[68:71], v[206:209], v[88:91]
	v_mfma_f32_16x16x32_bf16 v[132:135], v[158:161], v[178:181], v[132:135]
	v_mfma_f32_16x16x32_bf16 v[128:131], v[170:173], v[178:181], v[128:131]
	v_mfma_f32_16x16x32_bf16 v[116:119], v[158:161], v[186:189], v[116:119]
	v_mfma_f32_16x16x32_bf16 v[112:115], v[170:173], v[186:189], v[112:115]
	v_mfma_f32_16x16x32_bf16 v[100:103], v[158:161], v[194:197], v[100:103]
	v_mfma_f32_16x16x32_bf16 v[96:99], v[170:173], v[194:197], v[96:99]
	v_mfma_f32_16x16x32_bf16 v[84:87], v[158:161], v[202:205], v[84:87]
	v_mfma_f32_16x16x32_bf16 v[80:83], v[170:173], v[202:205], v[80:83]
	v_mfma_f32_16x16x32_bf16 v[132:135], v[166:169], v[182:185], v[132:135]
	v_mfma_f32_16x16x32_bf16 v[128:131], v[174:177], v[182:185], v[128:131]
	v_mfma_f32_16x16x32_bf16 v[116:119], v[166:169], v[190:193], v[116:119]
	v_mfma_f32_16x16x32_bf16 v[112:115], v[174:177], v[190:193], v[112:115]
	v_mfma_f32_16x16x32_bf16 v[100:103], v[166:169], v[198:201], v[100:103]
	v_mfma_f32_16x16x32_bf16 v[96:99], v[174:177], v[198:201], v[96:99]
	s_setprio 3
	s_barrier
; #define PG8_STAGE(bufoff, gbase, voff) do { _Pragma("unroll") for (int _i = 0; _i < 2; ++_i) \
;         __builtin_amdgcn_global_load_lds((const unsigned*)((const char*)(gbase) + (voff)[_i]), (PG8_LAS unsigned*)(lds + (bufoff) + ldsw + _i * 8192), 16, 0, 0); } while (0)
; #define PG8_LDA(dst, b, h) do { _Pragma("unroll") for (int m = 0; m < 4; ++m) _Pragma("unroll") for (int k = 0; k < 2; ++k) dst[m][k] = *(const PG8_LAS bf16x8*)(lds + PG8_SA(b, h) + aoff + m * 2048 + k * 1024); } while (0)
; #define PG8_MMA(ai, bj, At, Bt) do { __builtin_amdgcn_s_setprio(1); _Pragma("unroll") for (int m = 0; m < 4; ++m) _Pragma("unroll") for (int n = 0; n < 2; ++n) _Pragma("unroll") for (int k = 0; k < 2; ++k) \
;         acc[ai][bj][m][n] = __builtin_amdgcn_mfma_f32_16x16x32_bf16(Bt[n][k], At[m][k], acc[ai][bj][m][n], 0, 0, 0); __builtin_amdgcn_s_setprio(0); } while (0)
; #define PG8_WAIT_V(n) asm volatile("s_waitcnt vmcnt(" #n ")" ::: "memory")
; #define PG8_WAIT_L(n) asm volatile("s_waitcnt lgkmcnt(" #n ")" ::: "memory")
; #define PG8_BAR __builtin_amdgcn_s_barrier()
; #define PG8_SCHED __builtin_amdgcn_sched_barrier(0)
; template <class Epi, class Sched, bool ALIGN_EPI = false, bool SP2 = false>
; __device__ __forceinline__ void gemm_phase(PG8_LAS unsigned char* lds, const Gemm g, const Sched& S, const Epi& E, int tid_in) {
;     ...
;             PG8_WAIT_V(8); PG8_WAIT_L(0); PG8_BAR; PG8_MMA(0, 0, At, B0); PG8_MMA(0, 1, At, B1); PG8_BAR; PG8_SCHED;
;             PG8_LDA(At, 1, 1); PG8_STAGE(PG8_SB(1, 0), b3, voffB); PG8_STAGE(PG8_SB(1, 1), b3 + hstep, voffB); PG8_STAGE(PG8_SA(1, 0), a3, voffA);
;             PG8_WAIT_V(8); PG8_WAIT_L(0); PG8_BAR; PG8_MMA(1, 0, At, B0); PG8_MMA(1, 1, At, B1); PG8_BAR; PG8_SCHED;
	v_mfma_f32_16x16x32_bf16 v[84:87], v[166:169], v[206:209], v[84:87]
	v_mfma_f32_16x16x32_bf16 v[80:83], v[174:177], v[206:209], v[80:83]
	s_setprio 0
	s_add_i32 s2, s33, s35
	v_lshl_add_u64 v[210:211], v[210:211], 0, s[68:69]
	s_mov_b32 m0, s2
	ds_read_b128 v[178:181], v165 offset:49152
	ds_read_b128 v[182:185], v165 offset:50176
	ds_read_b128 v[186:189], v165 offset:51200
	ds_read_b128 v[190:193], v165 offset:52224
	ds_read_b128 v[194:197], v165 offset:53248
	ds_read_b128 v[198:201], v165 offset:54272
	ds_read_b128 v[202:205], v165 offset:55296
	ds_read_b128 v[206:209], v165 offset:56320
	global_load_lds_dwordx4 v[210:211], off
	s_add_i32 m0, s2, 0x2000
	s_add_u32 s2, s22, 0x40080
	v_lshl_add_u64 v[210:211], v[212:213], 0, s[68:69]
	s_addc_u32 s3, s23, 0
	s_add_i32 s22, s34, s35
	global_load_lds_dwordx4 v[210:211], off
	v_lshl_add_u64 v[210:211], s[2:3], 0, v[144:145]
	s_mov_b32 m0, s22
	s_nop 0
	global_load_lds_dwordx4 v[210:211], off
	v_lshl_add_u64 v[210:211], s[2:3], 0, v[148:149]
	s_add_i32 m0, s22, 0x2000
	s_nop 0
	global_load_lds_dwordx4 v[210:211], off
	v_lshl_add_u64 v[210:211], v[214:215], 0, s[68:69]
	s_mov_b32 m0, s41
	s_nop 0
	global_load_lds_dwordx4 v[210:211], off
	v_lshl_add_u64 v[210:211], v[216:217], 0, s[68:69]
	s_mov_b32 m0, s42
	s_nop 0
	global_load_lds_dwordx4 v[210:211], off
	s_waitcnt vmcnt(8)
	s_waitcnt lgkmcnt(0)
	s_barrier
	s_setprio 1
	s_waitcnt lgkmcnt(0)
	v_mfma_f32_16x16x32_bf16 v[76:79], v[56:59], v[178:181], v[76:79]
	v_mfma_f32_16x16x32_bf16 v[72:75], v[64:67], v[178:181], v[72:75]
	v_mfma_f32_16x16x32_bf16 v[44:47], v[56:59], v[186:189], v[44:47]
	v_mfma_f32_16x16x32_bf16 v[40:43], v[64:67], v[186:189], v[40:43]
	v_mfma_f32_16x16x32_bf16 v[28:31], v[56:59], v[194:197], v[28:31]
	v_mfma_f32_16x16x32_bf16 v[24:27], v[64:67], v[194:197], v[24:27]
	v_mfma_f32_16x16x32_bf16 v[12:15], v[56:59], v[202:205], v[12:15]
	v_mfma_f32_16x16x32_bf16 v[8:11], v[64:67], v[202:205], v[8:11]
	v_mfma_f32_16x16x32_bf16 v[76:79], v[60:63], v[182:185], v[76:79]
	v_mfma_f32_16x16x32_bf16 v[72:75], v[68:71], v[182:185], v[72:75]
	v_mfma_f32_16x16x32_bf16 v[44:47], v[60:63], v[190:193], v[44:47]
	v_mfma_f32_16x16x32_bf16 v[40:43], v[68:71], v[190:193], v[40:43]
	v_mfma_f32_16x16x32_bf16 v[28:31], v[60:63], v[198:201], v[28:31]
	v_mfma_f32_16x16x32_bf16 v[24:27], v[68:71], v[198:201], v[24:27]
	v_mfma_f32_16x16x32_bf16 v[12:15], v[60:63], v[206:209], v[12:15]
	v_mfma_f32_16x16x32_bf16 v[8:11], v[68:71], v[206:209], v[8:11]
	v_mfma_f32_16x16x32_bf16 v[48:51], v[158:161], v[178:181], v[48:51]
	v_mfma_f32_16x16x32_bf16 v[68:71], v[166:169], v[182:185], v[48:51]
	v_mfma_f32_16x16x32_bf16 v[48:51], v[170:173], v[178:181], v[52:55]
	v_mfma_f32_16x16x32_bf16 v[36:39], v[158:161], v[186:189], v[36:39]
	v_mfma_f32_16x16x32_bf16 v[32:35], v[170:173], v[186:189], v[32:35]
	v_mfma_f32_16x16x32_bf16 v[20:23], v[158:161], v[194:197], v[20:23]
	v_mfma_f32_16x16x32_bf16 v[16:19], v[170:173], v[194:197], v[16:19]
	v_mfma_f32_16x16x32_bf16 v[4:7], v[158:161], v[202:205], v[4:7]
	v_mfma_f32_16x16x32_bf16 v[0:3], v[170:173], v[202:205], v[0:3]
	v_mfma_f32_16x16x32_bf16 v[64:67], v[174:177], v[182:185], v[48:51]
	v_mfma_f32_16x16x32_bf16 v[36:39], v[166:169], v[190:193], v[36:39]
	v_mfma_f32_16x16x32_bf16 v[32:35], v[174:177], v[190:193], v[32:35]
	v_mfma_f32_16x16x32_bf16 v[20:23], v[166:169], v[198:201], v[20:23]
	v_mfma_f32_16x16x32_bf16 v[16:19], v[174:177], v[198:201], v[16:19]
	s_setprio 3
	s_barrier
	v_mfma_f32_16x16x32_bf16 v[4:7], v[166:169], v[206:209], v[4:7]
	v_mfma_f32_16x16x32_bf16 v[0:3], v[174:177], v[206:209], v[0:3]
	s_setprio 0
	s_add_i32 s49, s49, 2
	s_add_u32 s20, s20, 0x100
	s_addc_u32 s21, s21, 0
	s_add_u32 s47, s47, 0x100
	s_addc_u32 s48, s48, 0
	s_cmp_gt_u32 s49, 13
	s_cbranch_scc0 .LBB0_351
	s_and_b64 vcc, exec, s[6:7]
	s_cbranch_vccz .LBB0_354
	s_barrier
